# stack13: grid barriers issue the acquire L1 invalidate right after the arrival atomic returns (overlaps the wait) instead of after the release flag is seen
# speedup vs baseline: 1.0116x; 1.0116x over previous
; DI void grid_barrier_xcd(unsigned* bar, const unsigned gen, const unsigned my_xcc, const unsigned n_local, const unsigned n_xcds) {
;     ...
;     unsigned* xcnt = bar + 768 + 32 * my_xcc;
;     unsigned* top = bar + 640;
;     unsigned* rel = bar + 704;
;     const unsigned old = __hip_atomic_fetch_add(xcnt, 1u, __ATOMIC_RELAXED, __HIP_MEMORY_SCOPE_AGENT);
;     if (old + 1u == gen * n_local) {
;       __builtin_amdgcn_fence(__ATOMIC_RELEASE, "agent");
;       asm volatile("s_waitcnt vmcnt(0)" ::: "memory");
;       const unsigned t = __hip_atomic_fetch_add(top, 1u, __ATOMIC_RELAXED, __HIP_MEMORY_SCOPE_AGENT);
;       if (t + 1u == gen * n_xcds) __hip_atomic_store(rel, gen, __ATOMIC_RELAXED, __HIP_MEMORY_SCOPE_AGENT);
;     }
.LBB0_36:
	s_or_b64 exec, exec, s[10:11]
	s_waitcnt vmcnt(0)
	buffer_inv sc1
	v_readfirstlane_b32 s0, v2
	s_add_u32 s10, s72, 0x1ec00b00
	s_addc_u32 s11, s73, 0
	v_add3_u32 v1, s0, v1, 1
	v_cmp_eq_u32_e32 vcc, v1, v201
	s_and_saveexec_b64 s[12:13], vcc
	s_cbranch_execz .LBB0_41
	s_mov_b64 s[14:15], exec
	buffer_wbl2 sc1
	s_waitcnt vmcnt(0)
	v_mbcnt_lo_u32_b32 v1, s14, 0
	v_mbcnt_hi_u32_b32 v1, s15, v1
	v_cmp_eq_u32_e32 vcc, 0, v1
	s_and_saveexec_b64 s[16:17], vcc
	s_cbranch_execz .LBB0_39
	s_bcnt1_i32_b64 s0, s[14:15]
	v_mov_b32_e32 v2, 0x1ec00000
	v_mov_b32_e32 v3, s0
	global_atomic_add v2, v2, v3, s[72:73] offset:2560 sc0

; DI void grid_barrier_xcd(unsigned* bar, const unsigned gen, const unsigned my_xcc, const unsigned n_local, const unsigned n_xcds) {
;     ...
;     unsigned spins = 0;
;     while (__hip_atomic_load(rel, __ATOMIC_RELAXED, __HIP_MEMORY_SCOPE_AGENT) < gen) {
;       __builtin_amdgcn_s_sleep(1);
;       if (++spins > (1u << 24)) break;
;     }
;     __builtin_amdgcn_fence(__ATOMIC_ACQUIRE, "agent");
;     asm volatile("s_waitcnt vmcnt(0)" ::: "memory");
;   }
;   __syncthreads();
.LBB0_44:
	global_load_dword v2, v1, s[10:11] sc1
	s_mov_b64 s[12:13], -1
	s_waitcnt vmcnt(0)
	v_cmp_ne_u32_e32 vcc, 0, v2
	s_cbranch_vccnz .LBB0_43
	s_cmp_lg_u32 s0, 0
	s_sleep 1
	s_cbranch_scc0 .LBB0_42
	global_load_dword v2, v1, s[10:11] sc1
	s_waitcnt vmcnt(0)
	v_cmp_eq_u32_e32 vcc, 0, v2
	s_cbranch_vccz .LBB0_43
	s_sleep 1
	global_load_dword v2, v1, s[10:11] sc1
	s_waitcnt vmcnt(0)
	v_cmp_eq_u32_e32 vcc, 0, v2
	s_cbranch_vccz .LBB0_43
	s_sleep 1
	global_load_dword v2, v1, s[10:11] sc1
	s_waitcnt vmcnt(0)
	v_cmp_eq_u32_e32 vcc, 0, v2
	s_cbranch_vccz .LBB0_43
	s_sleep 1
	global_load_dword v2, v1, s[10:11] sc1
	s_waitcnt vmcnt(0)
	v_cmp_eq_u32_e32 vcc, 0, v2
	s_cbranch_vccz .LBB0_43
	s_sleep 1
	global_load_dword v2, v1, s[10:11] sc1
	s_waitcnt vmcnt(0)
	v_cmp_eq_u32_e32 vcc, 0, v2
	s_cbranch_vccz .LBB0_43
	s_sleep 1
	global_load_dword v2, v1, s[10:11] sc1
	s_waitcnt vmcnt(0)
	v_cmp_eq_u32_e32 vcc, 0, v2
	s_cbranch_vccz .LBB0_43
	s_sleep 1
	global_load_dword v2, v1, s[10:11] sc1
	s_waitcnt vmcnt(0)
	v_cmp_eq_u32_e32 vcc, 0, v2
	s_cbranch_vccz .LBB0_43
	s_sleep 1
	s_add_i32 s0, s0, -8
	s_mov_b64 s[12:13], 0
	s_branch .LBB0_43
.LBB0_54:
	s_waitcnt vmcnt(0)
.LBB0_55:
	s_or_b64 exec, exec, s[6:7]
	s_barrier
	s_mov_b32 s30, 1

; DI void grid_barrier_xcd(unsigned* bar, const unsigned gen, const unsigned my_xcc, const unsigned n_local, const unsigned n_xcds) {
;     ...
;     unsigned* xcnt = bar + 768 + 32 * my_xcc;
;     unsigned* top = bar + 640;
;     unsigned* rel = bar + 704;
;     const unsigned old = __hip_atomic_fetch_add(xcnt, 1u, __ATOMIC_RELAXED, __HIP_MEMORY_SCOPE_AGENT);
;     if (old + 1u == gen * n_local) {
;       __builtin_amdgcn_fence(__ATOMIC_RELEASE, "agent");
;       asm volatile("s_waitcnt vmcnt(0)" ::: "memory");
;       const unsigned t = __hip_atomic_fetch_add(top, 1u, __ATOMIC_RELAXED, __HIP_MEMORY_SCOPE_AGENT);
;       if (t + 1u == gen * n_xcds) __hip_atomic_store(rel, gen, __ATOMIC_RELAXED, __HIP_MEMORY_SCOPE_AGENT);
;     }
.LBB0_130:
	s_or_b64 exec, exec, s[10:11]
	s_waitcnt vmcnt(0)
	buffer_inv sc1
	v_readfirstlane_b32 s0, v2
	s_add_u32 s10, s72, 0x1ec00b00
	v_mul_lo_u32 v2, v201, s3
	v_add3_u32 v1, s0, v1, 1
	s_addc_u32 s11, s73, 0
	v_cmp_eq_u32_e32 vcc, v1, v2
	s_and_saveexec_b64 s[12:13], vcc
	s_cbranch_execz .LBB0_135
	s_mov_b64 s[14:15], exec
	buffer_wbl2 sc1
	s_waitcnt vmcnt(0)
	v_mbcnt_lo_u32_b32 v1, s14, 0
	v_mbcnt_hi_u32_b32 v1, s15, v1
	v_cmp_eq_u32_e32 vcc, 0, v1
	s_and_saveexec_b64 s[16:17], vcc
	s_cbranch_execz .LBB0_133
	s_bcnt1_i32_b64 s0, s[14:15]
	v_mov_b32_e32 v2, 0x1ec00000
	v_mov_b32_e32 v3, s0
	global_atomic_add v2, v2, v3, s[72:73] offset:2560 sc0

; DI void grid_barrier_xcd(unsigned* bar, const unsigned gen, const unsigned my_xcc, const unsigned n_local, const unsigned n_xcds) {
;     ...
;     unsigned spins = 0;
;     while (__hip_atomic_load(rel, __ATOMIC_RELAXED, __HIP_MEMORY_SCOPE_AGENT) < gen) {
;       __builtin_amdgcn_s_sleep(1);
;       if (++spins > (1u << 24)) break;
;     }
;     __builtin_amdgcn_fence(__ATOMIC_ACQUIRE, "agent");
;     asm volatile("s_waitcnt vmcnt(0)" ::: "memory");
;   }
;   __syncthreads();
.LBB0_138:
	global_load_dword v2, v1, s[10:11] sc1
	s_mov_b64 s[12:13], -1
	s_waitcnt vmcnt(0)
	v_cmp_lt_u32_e32 vcc, s30, v2
	s_cbranch_vccnz .LBB0_137
	s_cmp_lg_u32 s0, 0
	s_sleep 1
	s_cbranch_scc0 .LBB0_136
	global_load_dword v2, v1, s[10:11] sc1
	s_waitcnt vmcnt(0)
	v_cmp_ge_u32_e32 vcc, s30, v2
	s_cbranch_vccz .LBB0_137
	s_sleep 1
	global_load_dword v2, v1, s[10:11] sc1
	s_waitcnt vmcnt(0)
	v_cmp_ge_u32_e32 vcc, s30, v2
	s_cbranch_vccz .LBB0_137
	s_sleep 1
	global_load_dword v2, v1, s[10:11] sc1
	s_waitcnt vmcnt(0)
	v_cmp_ge_u32_e32 vcc, s30, v2
	s_cbranch_vccz .LBB0_137
	s_sleep 1
	global_load_dword v2, v1, s[10:11] sc1
	s_waitcnt vmcnt(0)
	v_cmp_ge_u32_e32 vcc, s30, v2
	s_cbranch_vccz .LBB0_137
	s_sleep 1
	global_load_dword v2, v1, s[10:11] sc1
	s_waitcnt vmcnt(0)
	v_cmp_ge_u32_e32 vcc, s30, v2
	s_cbranch_vccz .LBB0_137
	s_sleep 1
	global_load_dword v2, v1, s[10:11] sc1
	s_waitcnt vmcnt(0)
	v_cmp_ge_u32_e32 vcc, s30, v2
	s_cbranch_vccz .LBB0_137
	s_sleep 1
	global_load_dword v2, v1, s[10:11] sc1
	s_waitcnt vmcnt(0)
	v_cmp_ge_u32_e32 vcc, s30, v2
	s_cbranch_vccz .LBB0_137
	s_sleep 1
	s_add_i32 s0, s0, -8
	s_mov_b64 s[12:13], 0
	s_branch .LBB0_137
.LBB0_148:
	s_waitcnt vmcnt(0)
.LBB0_149:
	s_or_b64 exec, exec, s[6:7]
	s_barrier

; DI void grid_barrier_xcd(unsigned* bar, const unsigned gen, const unsigned my_xcc, const unsigned n_local, const unsigned n_xcds) {
;     ...
;     unsigned* xcnt = bar + 768 + 32 * my_xcc;
;     unsigned* top = bar + 640;
;     unsigned* rel = bar + 704;
;     const unsigned old = __hip_atomic_fetch_add(xcnt, 1u, __ATOMIC_RELAXED, __HIP_MEMORY_SCOPE_AGENT);
;     if (old + 1u == gen * n_local) {
;       __builtin_amdgcn_fence(__ATOMIC_RELEASE, "agent");
;       asm volatile("s_waitcnt vmcnt(0)" ::: "memory");
;       const unsigned t = __hip_atomic_fetch_add(top, 1u, __ATOMIC_RELAXED, __HIP_MEMORY_SCOPE_AGENT);
;       if (t + 1u == gen * n_xcds) __hip_atomic_store(rel, gen, __ATOMIC_RELAXED, __HIP_MEMORY_SCOPE_AGENT);
;     }
.LBB0_263:
	s_or_b64 exec, exec, s[10:11]
	s_waitcnt vmcnt(0)
	buffer_inv sc1
	v_readfirstlane_b32 s0, v2
	s_add_u32 s10, s72, 0x1ec00b00
	v_mul_lo_u32 v2, v201, s4
	v_add3_u32 v1, s0, v1, 1
	s_addc_u32 s11, s73, 0
	v_cmp_eq_u32_e32 vcc, v1, v2
	s_and_saveexec_b64 s[12:13], vcc
	s_cbranch_execz .LBB0_268
	s_mov_b64 s[14:15], exec
	buffer_wbl2 sc1
	s_waitcnt vmcnt(0)
	v_mbcnt_lo_u32_b32 v1, s14, 0
	v_mbcnt_hi_u32_b32 v1, s15, v1
	v_cmp_eq_u32_e32 vcc, 0, v1
	s_and_saveexec_b64 s[16:17], vcc
	s_cbranch_execz .LBB0_266
	s_bcnt1_i32_b64 s0, s[14:15]
	v_mov_b32_e32 v2, 0x1ec00000
	v_mov_b32_e32 v3, s0
	global_atomic_add v2, v2, v3, s[72:73] offset:2560 sc0

; DI void grid_barrier_xcd(unsigned* bar, const unsigned gen, const unsigned my_xcc, const unsigned n_local, const unsigned n_xcds) {
;     ...
;     unsigned spins = 0;
;     while (__hip_atomic_load(rel, __ATOMIC_RELAXED, __HIP_MEMORY_SCOPE_AGENT) < gen) {
;       __builtin_amdgcn_s_sleep(1);
;       if (++spins > (1u << 24)) break;
;     }
;     __builtin_amdgcn_fence(__ATOMIC_ACQUIRE, "agent");
;     asm volatile("s_waitcnt vmcnt(0)" ::: "memory");
;   }
;   __syncthreads();
.LBB0_271:
	global_load_dword v2, v1, s[10:11] sc1
	s_mov_b64 s[12:13], -1
	s_waitcnt vmcnt(0)
	v_cmp_lt_u32_e32 vcc, s3, v2
	s_cbranch_vccnz .LBB0_270
	s_cmp_lg_u32 s0, 0
	s_sleep 1
	s_cbranch_scc0 .LBB0_269
	global_load_dword v2, v1, s[10:11] sc1
	s_waitcnt vmcnt(0)
	v_cmp_ge_u32_e32 vcc, s3, v2
	s_cbranch_vccz .LBB0_270
	s_sleep 1
	global_load_dword v2, v1, s[10:11] sc1
	s_waitcnt vmcnt(0)
	v_cmp_ge_u32_e32 vcc, s3, v2
	s_cbranch_vccz .LBB0_270
	s_sleep 1
	global_load_dword v2, v1, s[10:11] sc1
	s_waitcnt vmcnt(0)
	v_cmp_ge_u32_e32 vcc, s3, v2
	s_cbranch_vccz .LBB0_270
	s_sleep 1
	global_load_dword v2, v1, s[10:11] sc1
	s_waitcnt vmcnt(0)
	v_cmp_ge_u32_e32 vcc, s3, v2
	s_cbranch_vccz .LBB0_270
	s_sleep 1
	global_load_dword v2, v1, s[10:11] sc1
	s_waitcnt vmcnt(0)
	v_cmp_ge_u32_e32 vcc, s3, v2
	s_cbranch_vccz .LBB0_270
	s_sleep 1
	global_load_dword v2, v1, s[10:11] sc1
	s_waitcnt vmcnt(0)
	v_cmp_ge_u32_e32 vcc, s3, v2
	s_cbranch_vccz .LBB0_270
	s_sleep 1
	global_load_dword v2, v1, s[10:11] sc1
	s_waitcnt vmcnt(0)
	v_cmp_ge_u32_e32 vcc, s3, v2
	s_cbranch_vccz .LBB0_270
	s_sleep 1
	s_add_i32 s0, s0, -8
	s_mov_b64 s[12:13], 0
	s_branch .LBB0_270
.LBB0_281:
	s_waitcnt vmcnt(0)
.LBB0_282:
	s_or_b64 exec, exec, s[6:7]
	s_barrier

; DI void grid_barrier_xcd(unsigned* bar, const unsigned gen, const unsigned my_xcc, const unsigned n_local, const unsigned n_xcds) {
;     ...
;     unsigned* xcnt = bar + 768 + 32 * my_xcc;
;     unsigned* top = bar + 640;
;     unsigned* rel = bar + 704;
;     const unsigned old = __hip_atomic_fetch_add(xcnt, 1u, __ATOMIC_RELAXED, __HIP_MEMORY_SCOPE_AGENT);
;     if (old + 1u == gen * n_local) {
;       __builtin_amdgcn_fence(__ATOMIC_RELEASE, "agent");
;       asm volatile("s_waitcnt vmcnt(0)" ::: "memory");
;       const unsigned t = __hip_atomic_fetch_add(top, 1u, __ATOMIC_RELAXED, __HIP_MEMORY_SCOPE_AGENT);
;       if (t + 1u == gen * n_xcds) __hip_atomic_store(rel, gen, __ATOMIC_RELAXED, __HIP_MEMORY_SCOPE_AGENT);
;     }
.LBB0_324:
	s_or_b64 exec, exec, s[8:9]
	s_waitcnt vmcnt(0)
	buffer_inv sc1
	v_readfirstlane_b32 s0, v2
	s_add_u32 s8, s72, 0x1ec00b00
	v_mul_lo_u32 v2, v201, s5
	v_add3_u32 v1, s0, v1, 1
	s_addc_u32 s9, s73, 0
	v_cmp_eq_u32_e32 vcc, v1, v2
	s_and_saveexec_b64 s[12:13], vcc
	s_cbranch_execz .LBB0_329
	s_mov_b64 s[14:15], exec
	buffer_wbl2 sc1
	s_waitcnt vmcnt(0)
	v_mbcnt_lo_u32_b32 v1, s14, 0
	v_mbcnt_hi_u32_b32 v1, s15, v1
	v_cmp_eq_u32_e32 vcc, 0, v1
	s_and_saveexec_b64 s[16:17], vcc
	s_cbranch_execz .LBB0_327
	s_bcnt1_i32_b64 s0, s[14:15]
	v_mov_b32_e32 v2, 0x1ec00000
	v_mov_b32_e32 v3, s0
	global_atomic_add v2, v2, v3, s[72:73] offset:2560 sc0

; DI void grid_barrier_xcd(unsigned* bar, const unsigned gen, const unsigned my_xcc, const unsigned n_local, const unsigned n_xcds) {
;     ...
;     unsigned spins = 0;
;     while (__hip_atomic_load(rel, __ATOMIC_RELAXED, __HIP_MEMORY_SCOPE_AGENT) < gen) {
;       __builtin_amdgcn_s_sleep(1);
;       if (++spins > (1u << 24)) break;
;     }
;     __builtin_amdgcn_fence(__ATOMIC_ACQUIRE, "agent");
;     asm volatile("s_waitcnt vmcnt(0)" ::: "memory");
;   }
;   __syncthreads();
.LBB0_332:
	global_load_dword v2, v1, s[8:9] sc1
	s_mov_b64 s[12:13], -1
	s_waitcnt vmcnt(0)
	v_cmp_lt_u32_e32 vcc, s4, v2
	s_cbranch_vccnz .LBB0_331
	s_cmp_lg_u32 s0, 0
	s_sleep 1
	s_cbranch_scc0 .LBB0_330
	global_load_dword v2, v1, s[8:9] sc1
	s_waitcnt vmcnt(0)
	v_cmp_ge_u32_e32 vcc, s4, v2
	s_cbranch_vccz .LBB0_331
	s_sleep 1
	global_load_dword v2, v1, s[8:9] sc1
	s_waitcnt vmcnt(0)
	v_cmp_ge_u32_e32 vcc, s4, v2
	s_cbranch_vccz .LBB0_331
	s_sleep 1
	global_load_dword v2, v1, s[8:9] sc1
	s_waitcnt vmcnt(0)
	v_cmp_ge_u32_e32 vcc, s4, v2
	s_cbranch_vccz .LBB0_331
	s_sleep 1
	global_load_dword v2, v1, s[8:9] sc1
	s_waitcnt vmcnt(0)
	v_cmp_ge_u32_e32 vcc, s4, v2
	s_cbranch_vccz .LBB0_331
	s_sleep 1
	global_load_dword v2, v1, s[8:9] sc1
	s_waitcnt vmcnt(0)
	v_cmp_ge_u32_e32 vcc, s4, v2
	s_cbranch_vccz .LBB0_331
	s_sleep 1
	global_load_dword v2, v1, s[8:9] sc1
	s_waitcnt vmcnt(0)
	v_cmp_ge_u32_e32 vcc, s4, v2
	s_cbranch_vccz .LBB0_331
	s_sleep 1
	global_load_dword v2, v1, s[8:9] sc1
	s_waitcnt vmcnt(0)
	v_cmp_ge_u32_e32 vcc, s4, v2
	s_cbranch_vccz .LBB0_331
	s_sleep 1
	s_add_i32 s0, s0, -8
	s_mov_b64 s[12:13], 0
	s_branch .LBB0_331
.LBB0_342:
	s_waitcnt vmcnt(0)
.LBB0_343:
	s_or_b64 exec, exec, s[6:7]
	s_barrier

; DI void grid_barrier_xcd(unsigned* bar, const unsigned gen, const unsigned my_xcc, const unsigned n_local, const unsigned n_xcds) {
;     ...
;     unsigned* xcnt = bar + 768 + 32 * my_xcc;
;     unsigned* top = bar + 640;
;     unsigned* rel = bar + 704;
;     const unsigned old = __hip_atomic_fetch_add(xcnt, 1u, __ATOMIC_RELAXED, __HIP_MEMORY_SCOPE_AGENT);
;     if (old + 1u == gen * n_local) {
;       __builtin_amdgcn_fence(__ATOMIC_RELEASE, "agent");
;       asm volatile("s_waitcnt vmcnt(0)" ::: "memory");
;       const unsigned t = __hip_atomic_fetch_add(top, 1u, __ATOMIC_RELAXED, __HIP_MEMORY_SCOPE_AGENT);
;       if (t + 1u == gen * n_xcds) __hip_atomic_store(rel, gen, __ATOMIC_RELAXED, __HIP_MEMORY_SCOPE_AGENT);
;     }
.LBB0_373:
	s_or_b64 exec, exec, s[8:9]
	s_waitcnt vmcnt(0)
	buffer_inv sc1
	v_readfirstlane_b32 s0, v2
	s_add_u32 s8, s72, 0x1ec00b00
	v_mul_lo_u32 v2, v201, s3
	v_add3_u32 v1, s0, v1, 1
	s_addc_u32 s9, s73, 0
	v_cmp_eq_u32_e32 vcc, v1, v2
	s_and_saveexec_b64 s[12:13], vcc
	s_cbranch_execz .LBB0_378
	s_mov_b64 s[14:15], exec
	buffer_wbl2 sc1
	s_waitcnt vmcnt(0)
	v_mbcnt_lo_u32_b32 v1, s14, 0
	v_mbcnt_hi_u32_b32 v1, s15, v1
	v_cmp_eq_u32_e32 vcc, 0, v1
	s_and_saveexec_b64 s[16:17], vcc
	s_cbranch_execz .LBB0_376
	s_bcnt1_i32_b64 s0, s[14:15]
	v_mov_b32_e32 v2, 0x1ec00000
	v_mov_b32_e32 v3, s0
	global_atomic_add v2, v2, v3, s[72:73] offset:2560 sc0

; DI void grid_barrier_xcd(unsigned* bar, const unsigned gen, const unsigned my_xcc, const unsigned n_local, const unsigned n_xcds) {
;     ...
;     unsigned spins = 0;
;     while (__hip_atomic_load(rel, __ATOMIC_RELAXED, __HIP_MEMORY_SCOPE_AGENT) < gen) {
;       __builtin_amdgcn_s_sleep(1);
;       if (++spins > (1u << 24)) break;
;     }
;     __builtin_amdgcn_fence(__ATOMIC_ACQUIRE, "agent");
;     asm volatile("s_waitcnt vmcnt(0)" ::: "memory");
;   }
;   __syncthreads();
.LBB0_381:
	global_load_dword v2, v1, s[8:9] sc1
	s_mov_b64 s[12:13], -1
	s_waitcnt vmcnt(0)
	v_cmp_lt_u32_e32 vcc, s5, v2
	s_cbranch_vccnz .LBB0_380
	s_cmp_lg_u32 s0, 0
	s_sleep 1
	s_cbranch_scc0 .LBB0_379
	global_load_dword v2, v1, s[8:9] sc1
	s_waitcnt vmcnt(0)
	v_cmp_ge_u32_e32 vcc, s5, v2
	s_cbranch_vccz .LBB0_380
	s_sleep 1
	global_load_dword v2, v1, s[8:9] sc1
	s_waitcnt vmcnt(0)
	v_cmp_ge_u32_e32 vcc, s5, v2
	s_cbranch_vccz .LBB0_380
	s_sleep 1
	global_load_dword v2, v1, s[8:9] sc1
	s_waitcnt vmcnt(0)
	v_cmp_ge_u32_e32 vcc, s5, v2
	s_cbranch_vccz .LBB0_380
	s_sleep 1
	global_load_dword v2, v1, s[8:9] sc1
	s_waitcnt vmcnt(0)
	v_cmp_ge_u32_e32 vcc, s5, v2
	s_cbranch_vccz .LBB0_380
	s_sleep 1
	global_load_dword v2, v1, s[8:9] sc1
	s_waitcnt vmcnt(0)
	v_cmp_ge_u32_e32 vcc, s5, v2
	s_cbranch_vccz .LBB0_380
	s_sleep 1
	global_load_dword v2, v1, s[8:9] sc1
	s_waitcnt vmcnt(0)
	v_cmp_ge_u32_e32 vcc, s5, v2
	s_cbranch_vccz .LBB0_380
	s_sleep 1
	global_load_dword v2, v1, s[8:9] sc1
	s_waitcnt vmcnt(0)
	v_cmp_ge_u32_e32 vcc, s5, v2
	s_cbranch_vccz .LBB0_380
	s_sleep 1
	s_add_i32 s0, s0, -8
	s_mov_b64 s[12:13], 0
	s_branch .LBB0_380
.LBB0_391:
	s_waitcnt vmcnt(0)
.LBB0_392:
	s_or_b64 exec, exec, s[6:7]
	s_barrier

; DI void grid_barrier_xcd(unsigned* bar, const unsigned gen, const unsigned my_xcc, const unsigned n_local, const unsigned n_xcds) {
;     ...
;     unsigned spins = 0;
;     while (__hip_atomic_load(rel, __ATOMIC_RELAXED, __HIP_MEMORY_SCOPE_AGENT) < gen) {
;       __builtin_amdgcn_s_sleep(1);
;       if (++spins > (1u << 24)) break;
;     }
;     __builtin_amdgcn_fence(__ATOMIC_ACQUIRE, "agent");
;     asm volatile("s_waitcnt vmcnt(0)" ::: "memory");
;   }
;   __syncthreads();
.LBB0_441:
	global_load_dword v2, v1, s[10:11] sc1
	s_mov_b64 s[12:13], -1
	s_waitcnt vmcnt(0)
	v_cmp_lt_u32_e32 vcc, s3, v2
	s_cbranch_vccnz .LBB0_440
	s_cmp_lg_u32 s0, 0
	s_sleep 1
	s_cbranch_scc0 .LBB0_439
	global_load_dword v2, v1, s[10:11] sc1
	s_waitcnt vmcnt(0)
	v_cmp_ge_u32_e32 vcc, s3, v2
	s_cbranch_vccz .LBB0_440
	s_sleep 1
	global_load_dword v2, v1, s[10:11] sc1
	s_waitcnt vmcnt(0)
	v_cmp_ge_u32_e32 vcc, s3, v2
	s_cbranch_vccz .LBB0_440
	s_sleep 1
	global_load_dword v2, v1, s[10:11] sc1
	s_waitcnt vmcnt(0)
	v_cmp_ge_u32_e32 vcc, s3, v2
	s_cbranch_vccz .LBB0_440
	s_sleep 1
	global_load_dword v2, v1, s[10:11] sc1
	s_waitcnt vmcnt(0)
	v_cmp_ge_u32_e32 vcc, s3, v2
	s_cbranch_vccz .LBB0_440
	s_sleep 1
	global_load_dword v2, v1, s[10:11] sc1
	s_waitcnt vmcnt(0)
	v_cmp_ge_u32_e32 vcc, s3, v2
	s_cbranch_vccz .LBB0_440
	s_sleep 1
	global_load_dword v2, v1, s[10:11] sc1
	s_waitcnt vmcnt(0)
	v_cmp_ge_u32_e32 vcc, s3, v2
	s_cbranch_vccz .LBB0_440
	s_sleep 1
	global_load_dword v2, v1, s[10:11] sc1
	s_waitcnt vmcnt(0)
	v_cmp_ge_u32_e32 vcc, s3, v2
	s_cbranch_vccz .LBB0_440
	s_sleep 1
	s_add_i32 s0, s0, -8
	s_mov_b64 s[12:13], 0
	s_branch .LBB0_440
.LBB0_451:
	s_waitcnt vmcnt(0)
.LBB0_452:
	s_or_b64 exec, exec, s[6:7]
	s_barrier

; DI void grid_barrier_xcd(unsigned* bar, const unsigned gen, const unsigned my_xcc, const unsigned n_local, const unsigned n_xcds) {
;     ...
;     unsigned* xcnt = bar + 768 + 32 * my_xcc;
;     unsigned* top = bar + 640;
;     unsigned* rel = bar + 704;
;     const unsigned old = __hip_atomic_fetch_add(xcnt, 1u, __ATOMIC_RELAXED, __HIP_MEMORY_SCOPE_AGENT);
;     if (old + 1u == gen * n_local) {
;       __builtin_amdgcn_fence(__ATOMIC_RELEASE, "agent");
;       asm volatile("s_waitcnt vmcnt(0)" ::: "memory");
;       const unsigned t = __hip_atomic_fetch_add(top, 1u, __ATOMIC_RELAXED, __HIP_MEMORY_SCOPE_AGENT);
;       if (t + 1u == gen * n_xcds) __hip_atomic_store(rel, gen, __ATOMIC_RELAXED, __HIP_MEMORY_SCOPE_AGENT);
;     }
.LBB0_482:
	s_or_b64 exec, exec, s[10:11]
	s_waitcnt vmcnt(0)
	buffer_inv sc1
	v_readfirstlane_b32 s0, v3
	s_add_u32 s10, s72, 0x1ec00b00
	v_mul_lo_u32 v3, v201, s5
	v_add3_u32 v2, s0, v2, 1
	s_addc_u32 s11, s73, 0
	v_cmp_eq_u32_e32 vcc, v2, v3
	s_and_saveexec_b64 s[12:13], vcc
	s_cbranch_execz .LBB0_487
	s_mov_b64 s[14:15], exec
	buffer_wbl2 sc1
	s_waitcnt vmcnt(0)
	v_mbcnt_lo_u32_b32 v2, s14, 0
	v_mbcnt_hi_u32_b32 v2, s15, v2
	v_cmp_eq_u32_e32 vcc, 0, v2
	s_and_saveexec_b64 s[16:17], vcc
	s_cbranch_execz .LBB0_485
	s_bcnt1_i32_b64 s0, s[14:15]
	v_mov_b32_e32 v3, 0x1ec00000
	v_mov_b32_e32 v4, s0
	global_atomic_add v3, v3, v4, s[72:73] offset:2560 sc0

; DI void grid_barrier_xcd(unsigned* bar, const unsigned gen, const unsigned my_xcc, const unsigned n_local, const unsigned n_xcds) {
;     ...
;     unsigned spins = 0;
;     while (__hip_atomic_load(rel, __ATOMIC_RELAXED, __HIP_MEMORY_SCOPE_AGENT) < gen) {
;       __builtin_amdgcn_s_sleep(1);
;       if (++spins > (1u << 24)) break;
;     }
;     __builtin_amdgcn_fence(__ATOMIC_ACQUIRE, "agent");
;     asm volatile("s_waitcnt vmcnt(0)" ::: "memory");
;   }
;   __syncthreads();
.LBB0_490:
	global_load_dword v3, v2, s[10:11] sc1
	s_mov_b64 s[12:13], -1
	s_waitcnt vmcnt(0)
	v_cmp_lt_u32_e32 vcc, s4, v3
	s_cbranch_vccnz .LBB0_489
	s_cmp_lg_u32 s0, 0
	s_sleep 1
	s_cbranch_scc0 .LBB0_488
	global_load_dword v3, v2, s[10:11] sc1
	s_waitcnt vmcnt(0)
	v_cmp_ge_u32_e32 vcc, s4, v3
	s_cbranch_vccz .LBB0_489
	s_sleep 1
	global_load_dword v3, v2, s[10:11] sc1
	s_waitcnt vmcnt(0)
	v_cmp_ge_u32_e32 vcc, s4, v3
	s_cbranch_vccz .LBB0_489
	s_sleep 1
	global_load_dword v3, v2, s[10:11] sc1
	s_waitcnt vmcnt(0)
	v_cmp_ge_u32_e32 vcc, s4, v3
	s_cbranch_vccz .LBB0_489
	s_sleep 1
	global_load_dword v3, v2, s[10:11] sc1
	s_waitcnt vmcnt(0)
	v_cmp_ge_u32_e32 vcc, s4, v3
	s_cbranch_vccz .LBB0_489
	s_sleep 1
	global_load_dword v3, v2, s[10:11] sc1
	s_waitcnt vmcnt(0)
	v_cmp_ge_u32_e32 vcc, s4, v3
	s_cbranch_vccz .LBB0_489
	s_sleep 1
	global_load_dword v3, v2, s[10:11] sc1
	s_waitcnt vmcnt(0)
	v_cmp_ge_u32_e32 vcc, s4, v3
	s_cbranch_vccz .LBB0_489
	s_sleep 1
	global_load_dword v3, v2, s[10:11] sc1
	s_waitcnt vmcnt(0)
	v_cmp_ge_u32_e32 vcc, s4, v3
	s_cbranch_vccz .LBB0_489
	s_sleep 1
	s_add_i32 s0, s0, -8
	s_mov_b64 s[12:13], 0
	s_branch .LBB0_489
.LBB0_500:
	s_waitcnt vmcnt(0)
.LBB0_501:
	s_or_b64 exec, exec, s[6:7]
	s_barrier

; DI void grid_barrier_xcd(unsigned* bar, const unsigned gen, const unsigned my_xcc, const unsigned n_local, const unsigned n_xcds) {
;     ...
;     unsigned* xcnt = bar + 768 + 32 * my_xcc;
;     unsigned* top = bar + 640;
;     unsigned* rel = bar + 704;
;     const unsigned old = __hip_atomic_fetch_add(xcnt, 1u, __ATOMIC_RELAXED, __HIP_MEMORY_SCOPE_AGENT);
;     if (old + 1u == gen * n_local) {
;       __builtin_amdgcn_fence(__ATOMIC_RELEASE, "agent");
;       asm volatile("s_waitcnt vmcnt(0)" ::: "memory");
;       const unsigned t = __hip_atomic_fetch_add(top, 1u, __ATOMIC_RELAXED, __HIP_MEMORY_SCOPE_AGENT);
;       if (t + 1u == gen * n_xcds) __hip_atomic_store(rel, gen, __ATOMIC_RELAXED, __HIP_MEMORY_SCOPE_AGENT);
;     }
.LBB0_544:
	s_or_b64 exec, exec, s[10:11]
	s_waitcnt vmcnt(0)
	buffer_inv sc1
	v_readfirstlane_b32 s0, v3
	s_add_u32 s10, s72, 0x1ec00b00
	v_mul_lo_u32 v3, v201, s3
	v_add3_u32 v2, s0, v2, 1
	s_addc_u32 s11, s73, 0
	v_cmp_eq_u32_e32 vcc, v2, v3
	s_and_saveexec_b64 s[12:13], vcc
	s_cbranch_execz .LBB0_549
	s_mov_b64 s[14:15], exec
	buffer_wbl2 sc1
	s_waitcnt vmcnt(0)
	v_mbcnt_lo_u32_b32 v2, s14, 0
	v_mbcnt_hi_u32_b32 v2, s15, v2
	v_cmp_eq_u32_e32 vcc, 0, v2
	s_and_saveexec_b64 s[16:17], vcc
	s_cbranch_execz .LBB0_547
	s_bcnt1_i32_b64 s0, s[14:15]
	v_mov_b32_e32 v3, 0x1ec00000
	v_mov_b32_e32 v4, s0
	global_atomic_add v3, v3, v4, s[72:73] offset:2560 sc0

; DI void grid_barrier_xcd(unsigned* bar, const unsigned gen, const unsigned my_xcc, const unsigned n_local, const unsigned n_xcds) {
;     ...
;     unsigned spins = 0;
;     while (__hip_atomic_load(rel, __ATOMIC_RELAXED, __HIP_MEMORY_SCOPE_AGENT) < gen) {
;       __builtin_amdgcn_s_sleep(1);
;       if (++spins > (1u << 24)) break;
;     }
;     __builtin_amdgcn_fence(__ATOMIC_ACQUIRE, "agent");
;     asm volatile("s_waitcnt vmcnt(0)" ::: "memory");
;   }
;   __syncthreads();
.LBB0_552:
	global_load_dword v3, v2, s[10:11] sc1
	s_mov_b64 s[12:13], -1
	s_waitcnt vmcnt(0)
	v_cmp_lt_u32_e32 vcc, s5, v3
	s_cbranch_vccnz .LBB0_551
	s_cmp_lg_u32 s0, 0
	s_sleep 1
	s_cbranch_scc0 .LBB0_550
	global_load_dword v3, v2, s[10:11] sc1
	s_waitcnt vmcnt(0)
	v_cmp_ge_u32_e32 vcc, s5, v3
	s_cbranch_vccz .LBB0_551
	s_sleep 1
	global_load_dword v3, v2, s[10:11] sc1
	s_waitcnt vmcnt(0)
	v_cmp_ge_u32_e32 vcc, s5, v3
	s_cbranch_vccz .LBB0_551
	s_sleep 1
	global_load_dword v3, v2, s[10:11] sc1
	s_waitcnt vmcnt(0)
	v_cmp_ge_u32_e32 vcc, s5, v3
	s_cbranch_vccz .LBB0_551
	s_sleep 1
	global_load_dword v3, v2, s[10:11] sc1
	s_waitcnt vmcnt(0)
	v_cmp_ge_u32_e32 vcc, s5, v3
	s_cbranch_vccz .LBB0_551
	s_sleep 1
	global_load_dword v3, v2, s[10:11] sc1
	s_waitcnt vmcnt(0)
	v_cmp_ge_u32_e32 vcc, s5, v3
	s_cbranch_vccz .LBB0_551
	s_sleep 1
	global_load_dword v3, v2, s[10:11] sc1
	s_waitcnt vmcnt(0)
	v_cmp_ge_u32_e32 vcc, s5, v3
	s_cbranch_vccz .LBB0_551
	s_sleep 1
	global_load_dword v3, v2, s[10:11] sc1
	s_waitcnt vmcnt(0)
	v_cmp_ge_u32_e32 vcc, s5, v3
	s_cbranch_vccz .LBB0_551
	s_sleep 1
	s_add_i32 s0, s0, -8
	s_mov_b64 s[12:13], 0
	s_branch .LBB0_551
.LBB0_562:
	s_waitcnt vmcnt(0)
.LBB0_563:
	s_or_b64 exec, exec, s[6:7]
	s_barrier

; DI void grid_barrier_xcd(unsigned* bar, const unsigned gen, const unsigned my_xcc, const unsigned n_local, const unsigned n_xcds) {
;     ...
;     unsigned* xcnt = bar + 768 + 32 * my_xcc;
;     unsigned* top = bar + 640;
;     unsigned* rel = bar + 704;
;     const unsigned old = __hip_atomic_fetch_add(xcnt, 1u, __ATOMIC_RELAXED, __HIP_MEMORY_SCOPE_AGENT);
;     if (old + 1u == gen * n_local) {
;       __builtin_amdgcn_fence(__ATOMIC_RELEASE, "agent");
;       asm volatile("s_waitcnt vmcnt(0)" ::: "memory");
;       const unsigned t = __hip_atomic_fetch_add(top, 1u, __ATOMIC_RELAXED, __HIP_MEMORY_SCOPE_AGENT);
;       if (t + 1u == gen * n_xcds) __hip_atomic_store(rel, gen, __ATOMIC_RELAXED, __HIP_MEMORY_SCOPE_AGENT);
;     }
.LBB0_591:
	s_or_b64 exec, exec, s[4:5]
	s_add_u32 s4, s72, 0x1ec00b00
	s_addc_u32 s5, s73, 0
	s_add_i32 s0, s3, 1
	s_waitcnt vmcnt(0)
	buffer_inv sc1
	v_readfirstlane_b32 s1, v2
	v_mul_lo_u32 v2, v201, s0
	s_nop 0
	v_add3_u32 v1, s1, v1, 1
	v_cmp_eq_u32_e32 vcc, v1, v2
	s_and_saveexec_b64 s[10:11], vcc
	s_cbranch_execz .LBB0_596
	s_mov_b64 s[12:13], exec
	buffer_wbl2 sc1
	s_waitcnt vmcnt(0)
	v_mbcnt_lo_u32_b32 v1, s12, 0
	v_mbcnt_hi_u32_b32 v1, s13, v1
	v_cmp_eq_u32_e32 vcc, 0, v1
	s_and_saveexec_b64 s[14:15], vcc
	s_cbranch_execz .LBB0_594
	s_bcnt1_i32_b64 s1, s[12:13]
	v_mov_b32_e32 v2, 0x1ec00000
	v_mov_b32_e32 v3, s1
	global_atomic_add v2, v2, v3, s[72:73] offset:2560 sc0

; DI void grid_barrier_xcd(unsigned* bar, const unsigned gen, const unsigned my_xcc, const unsigned n_local, const unsigned n_xcds) {
;     ...
;     unsigned spins = 0;
;     while (__hip_atomic_load(rel, __ATOMIC_RELAXED, __HIP_MEMORY_SCOPE_AGENT) < gen) {
;       __builtin_amdgcn_s_sleep(1);
;       if (++spins > (1u << 24)) break;
;     }
;     __builtin_amdgcn_fence(__ATOMIC_ACQUIRE, "agent");
;     asm volatile("s_waitcnt vmcnt(0)" ::: "memory");
;   }
;   __syncthreads();
.LBB0_599:
	global_load_dword v2, v1, s[4:5] sc1
	s_mov_b64 s[10:11], -1
	s_waitcnt vmcnt(0)
	v_cmp_lt_u32_e32 vcc, s3, v2
	s_cbranch_vccnz .LBB0_598
	s_cmp_lg_u32 s0, 0
	s_sleep 1
	s_cbranch_scc0 .LBB0_597
	global_load_dword v2, v1, s[4:5] sc1
	s_waitcnt vmcnt(0)
	v_cmp_ge_u32_e32 vcc, s3, v2
	s_cbranch_vccz .LBB0_598
	s_sleep 1
	global_load_dword v2, v1, s[4:5] sc1
	s_waitcnt vmcnt(0)
	v_cmp_ge_u32_e32 vcc, s3, v2
	s_cbranch_vccz .LBB0_598
	s_sleep 1
	global_load_dword v2, v1, s[4:5] sc1
	s_waitcnt vmcnt(0)
	v_cmp_ge_u32_e32 vcc, s3, v2
	s_cbranch_vccz .LBB0_598
	s_sleep 1
	global_load_dword v2, v1, s[4:5] sc1
	s_waitcnt vmcnt(0)
	v_cmp_ge_u32_e32 vcc, s3, v2
	s_cbranch_vccz .LBB0_598
	s_sleep 1
	global_load_dword v2, v1, s[4:5] sc1
	s_waitcnt vmcnt(0)
	v_cmp_ge_u32_e32 vcc, s3, v2
	s_cbranch_vccz .LBB0_598
	s_sleep 1
	global_load_dword v2, v1, s[4:5] sc1
	s_waitcnt vmcnt(0)
	v_cmp_ge_u32_e32 vcc, s3, v2
	s_cbranch_vccz .LBB0_598
	s_sleep 1
	global_load_dword v2, v1, s[4:5] sc1
	s_waitcnt vmcnt(0)
	v_cmp_ge_u32_e32 vcc, s3, v2
	s_cbranch_vccz .LBB0_598
	s_sleep 1
	s_add_i32 s0, s0, -8
	s_mov_b64 s[10:11], 0
	s_branch .LBB0_598
.LBB0_609:
	s_waitcnt vmcnt(0)
.LBB0_610:
	s_or_b64 exec, exec, s[6:7]
	s_barrier
